# v9b plus the first grid barrier's census loads issued back to back (one wait instead of ten dependent round trips)
# baseline (speedup 1.0000x reference)
; __device__ __forceinline__ unsigned xb_ld(unsigned* p)              { return __hip_atomic_load(p, __ATOMIC_RELAXED, __HIP_MEMORY_SCOPE_AGENT); }
; __device__ __forceinline__ void xcd_barrier_complete(unsigned* bar, unsigned x, unsigned& nloc, unsigned& nx) {
;     const unsigned G = gridDim.x * gridDim.y * gridDim.z;
;     unsigned sum, cnt, mine, sp = 0u;
;     for (;;) {
;         sum = 0u; cnt = 0u; mine = 0u;
; #pragma unroll
;         for (unsigned j = 0; j < 16; ++j) { const unsigned c = xb_ld(&bar[XB_XCNT(j)]); sum += c; cnt += (c > 0u) ? 1u : 0u; mine = (j == x) ? c : mine; }
;         if (sum == G) break;
;         __builtin_amdgcn_s_sleep(1);
;         if ((++sp & 255u) == 0u) { if (xb_ld(&bar[XB_TMO])) break; if (sp > XB_SPIN_CAP) { atomicAdd(&bar[XB_TMO], 1u); break; } }
;     }
;     nloc = mine > 0u ? mine : 1u; nx = cnt > 0u ? cnt : 1u;
; }
.LBB0_755:
	v_readlane_b32 s0, v253, 5
	v_readlane_b32 s1, v253, 6
	global_load_dword v4, v3, s[92:93] sc1
	global_load_dword v2, v3, s[94:95] sc1
	s_mov_b64 s[26:27], -1
	s_nop 1
	global_load_dword v5, v3, s[0:1] sc1
	v_readlane_b32 s0, v253, 7
	v_readlane_b32 s1, v253, 8
	s_nop 4
	global_load_dword v6, v3, s[0:1] sc1
	v_readlane_b32 s0, v253, 9
	v_readlane_b32 s1, v253, 10
	s_nop 4
	global_load_dword v7, v3, s[0:1] sc1
	v_readlane_b32 s0, v253, 11
	v_readlane_b32 s1, v253, 12
	s_nop 4
	global_load_dword v8, v3, s[0:1] sc1
	v_readlane_b32 s0, v253, 13
	v_readlane_b32 s1, v253, 14
	s_nop 4
	global_load_dword v9, v3, s[0:1] sc1
	v_readlane_b32 s0, v253, 15
	v_readlane_b32 s1, v253, 16
	s_nop 4
	global_load_dword v10, v3, s[0:1] sc1
	v_readlane_b32 s0, v253, 17
	v_readlane_b32 s1, v253, 18
	s_nop 4
	global_load_dword v11, v3, s[0:1] sc1
	v_readlane_b32 s0, v253, 19
	v_readlane_b32 s1, v253, 20
	s_nop 4
	global_load_dword v12, v3, s[0:1] sc1
	v_readlane_b32 s0, v253, 21
	v_readlane_b32 s1, v253, 22
	s_nop 4
	global_load_dword v13, v3, s[0:1] sc1
	v_readlane_b32 s0, v253, 23
	v_readlane_b32 s1, v253, 24
	s_nop 4
	global_load_dword v14, v3, s[0:1] sc1
	v_readlane_b32 s0, v253, 25
	v_readlane_b32 s1, v253, 26
	s_nop 4
	global_load_dword v15, v3, s[0:1] sc1
	global_load_dword v16, v3, s[14:15] sc1
	global_load_dword v17, v3, s[16:17] sc1
	global_load_dword v18, v3, s[18:19] sc1
	s_mov_b64 s[0:1], -1
	s_waitcnt vmcnt(4)
	v_add_u32_e32 v1, v2, v4
	v_add_u32_e32 v1, v1, v5
	v_add_u32_e32 v1, v1, v6
	v_add_u32_e32 v1, v1, v7
	v_add_u32_e32 v1, v1, v8
	v_add_u32_e32 v1, v1, v9
	v_add_u32_e32 v1, v1, v10
	v_add_u32_e32 v1, v1, v11
	v_add_u32_e32 v1, v1, v12
	v_add_u32_e32 v1, v1, v13
	v_add_u32_e32 v1, v1, v14
	s_waitcnt vmcnt(3)
	v_add_u32_e32 v1, v1, v15
	s_waitcnt vmcnt(2)
	v_add_u32_e32 v1, v1, v16
	s_waitcnt vmcnt(1)
	v_add_u32_e32 v1, v1, v17
	s_waitcnt vmcnt(0)
	v_add_u32_e32 v1, v1, v18
	v_cmp_eq_u32_e32 vcc, s5, v1
	s_cbranch_vccnz .LBB0_754
	s_and_b32 s0, s6, 0xff
	s_cmp_eq_u32 s0, 0
	s_mov_b64 s[0:1], -1
	s_mov_b64 s[36:37], -1
	s_sleep 1
	s_cbranch_scc1 .LBB0_759
	s_and_b64 vcc, exec, s[36:37]
	s_cbranch_vccz .LBB0_754
